# grid barrier: first-arriving block of each XCD issues an early un-waited L2 write-back so the last arriver's flush is short
# baseline (speedup 1.0000x reference)
.LBB0_53:
	s_or_b64 exec, exec, s[8:9]
	v_cvt_f32_u32_e32 v4, v2
	s_waitcnt vmcnt(0)
	v_readfirstlane_b32 s4, v3
	v_sub_u32_e32 v3, 0, v2
	v_rcp_iflag_f32_e32 v4, v4
	v_add_u32_e32 v5, s4, v0
	v_mul_f32_e32 v4, 0x4f7ffffe, v4
	v_cvt_u32_f32_e32 v4, v4
	v_mul_lo_u32 v0, v3, v4
	v_mul_hi_u32 v0, v4, v0
	v_add_u32_e32 v0, v4, v0
	v_mul_hi_u32 v0, v5, v0
	v_mul_lo_u32 v3, v0, v2
	v_sub_u32_e32 v3, v5, v3
	v_add_u32_e32 v4, 1, v0
	v_cmp_ge_u32_e32 vcc, v3, v2
	s_nop 1
	v_cndmask_b32_e32 v0, v0, v4, vcc
	v_sub_u32_e32 v4, v3, v2
	v_cndmask_b32_e32 v3, v3, v4, vcc
	v_add_u32_e32 v4, 1, v0
	v_cmp_ge_u32_e32 vcc, v3, v2
	v_add_u32_e32 v3, 1, v5
	s_nop 0
	v_cndmask_b32_e32 v0, v0, v4, vcc
	v_mul_lo_u32 v4, v2, v0
	v_add_u32_e32 v2, v4, v2
	v_cmp_eq_u32_e32 vcc, v5, v4
	s_and_saveexec_b64 s[98:99], vcc
	s_cbranch_execz .Lmy_fw_0
	buffer_wbl2 sc1
.Lmy_fw_0:
	s_or_b64 exec, exec, s[98:99]
	v_cmp_ne_u32_e32 vcc, v3, v2
	s_and_saveexec_b64 s[4:5], vcc
	s_xor_b64 s[4:5], exec, s[4:5]
	s_cbranch_execz .LBB0_67
	s_waitcnt lgkmcnt(0)
	v_mov_b32_e32 v1, 0x2000
	global_load_dword v1, v1, s[2:3] offset:1024 sc1
	s_add_u32 s12, s2, 0x2400
	s_addc_u32 s13, s3, 0
	s_waitcnt vmcnt(0)
	v_cmp_eq_u32_e32 vcc, v1, v0
	s_and_saveexec_b64 s[8:9], vcc
	s_cbranch_execz .LBB0_66
	s_add_u32 s10, s28, 0x163fc300
	s_addc_u32 s11, s29, 0
	s_mov_b32 s24, 1
	s_mov_b64 s[14:15], 0
	v_mov_b32_e32 v1, 0
	s_branch .LBB0_57

.LBB0_173:
	s_or_b64 exec, exec, s[8:9]
	v_cvt_f32_u32_e32 v4, v2
	s_waitcnt vmcnt(0)
	v_readfirstlane_b32 s6, v3
	v_sub_u32_e32 v3, 0, v2
	v_rcp_iflag_f32_e32 v4, v4
	v_add_u32_e32 v5, s6, v0
	v_mul_f32_e32 v4, 0x4f7ffffe, v4
	v_cvt_u32_f32_e32 v4, v4
	v_mul_lo_u32 v0, v3, v4
	v_mul_hi_u32 v0, v4, v0
	v_add_u32_e32 v0, v4, v0
	v_mul_hi_u32 v0, v5, v0
	v_mul_lo_u32 v3, v0, v2
	v_sub_u32_e32 v3, v5, v3
	v_add_u32_e32 v4, 1, v0
	v_cmp_ge_u32_e32 vcc, v3, v2
	s_nop 1
	v_cndmask_b32_e32 v0, v0, v4, vcc
	v_sub_u32_e32 v4, v3, v2
	v_cndmask_b32_e32 v3, v3, v4, vcc
	v_add_u32_e32 v4, 1, v0
	v_cmp_ge_u32_e32 vcc, v3, v2
	v_add_u32_e32 v3, 1, v5
	s_nop 0
	v_cndmask_b32_e32 v0, v0, v4, vcc
	v_mul_lo_u32 v4, v2, v0
	v_add_u32_e32 v2, v4, v2
	v_cmp_eq_u32_e32 vcc, v5, v4
	s_and_saveexec_b64 s[98:99], vcc
	s_cbranch_execz .Lmy_fw_1
	buffer_wbl2 sc1
.Lmy_fw_1:
	s_or_b64 exec, exec, s[98:99]
	v_cmp_ne_u32_e32 vcc, v3, v2
	s_and_saveexec_b64 s[6:7], vcc
	s_xor_b64 s[6:7], exec, s[6:7]
	s_cbranch_execz .LBB0_187
	s_waitcnt lgkmcnt(0)
	v_mov_b32_e32 v1, 0x2000
	global_load_dword v1, v1, s[4:5] offset:1024 sc1
	s_add_u32 s12, s4, 0x2400
	s_addc_u32 s13, s5, 0
	s_waitcnt vmcnt(0)
	v_cmp_eq_u32_e32 vcc, v1, v0
	s_and_saveexec_b64 s[8:9], vcc
	s_cbranch_execz .LBB0_186
	s_add_u32 s10, s28, 0x163fc300
	s_addc_u32 s11, s29, 0
	s_mov_b32 s24, 1
	s_mov_b64 s[14:15], 0
	v_mov_b32_e32 v1, 0
	s_branch .LBB0_177

.LBB0_242:
	s_or_b64 exec, exec, s[6:7]
	v_cvt_f32_u32_e32 v4, v2
	s_waitcnt vmcnt(0)
	v_readfirstlane_b32 s4, v3
	v_sub_u32_e32 v3, 0, v2
	v_rcp_iflag_f32_e32 v4, v4
	v_add_u32_e32 v5, s4, v0
	v_mul_f32_e32 v4, 0x4f7ffffe, v4
	v_cvt_u32_f32_e32 v4, v4
	v_mul_lo_u32 v0, v3, v4
	v_mul_hi_u32 v0, v4, v0
	v_add_u32_e32 v0, v4, v0
	v_mul_hi_u32 v0, v5, v0
	v_mul_lo_u32 v3, v0, v2
	v_sub_u32_e32 v3, v5, v3
	v_add_u32_e32 v4, 1, v0
	v_cmp_ge_u32_e32 vcc, v3, v2
	s_nop 1
	v_cndmask_b32_e32 v0, v0, v4, vcc
	v_sub_u32_e32 v4, v3, v2
	v_cndmask_b32_e32 v3, v3, v4, vcc
	v_add_u32_e32 v4, 1, v0
	v_cmp_ge_u32_e32 vcc, v3, v2
	v_add_u32_e32 v3, 1, v5
	s_nop 0
	v_cndmask_b32_e32 v0, v0, v4, vcc
	v_mul_lo_u32 v4, v2, v0
	v_add_u32_e32 v2, v4, v2
	v_cmp_eq_u32_e32 vcc, v5, v4
	s_and_saveexec_b64 s[98:99], vcc
	s_cbranch_execz .Lmy_fw_2
	buffer_wbl2 sc1
.Lmy_fw_2:
	s_or_b64 exec, exec, s[98:99]
	v_cmp_ne_u32_e32 vcc, v3, v2
	s_and_saveexec_b64 s[4:5], vcc
	s_xor_b64 s[4:5], exec, s[4:5]
	s_cbranch_execz .LBB0_256
	s_waitcnt lgkmcnt(0)
	v_mov_b32_e32 v1, 0x2000
	global_load_dword v1, v1, s[2:3] offset:1024 sc1
	s_add_u32 s10, s2, 0x2400
	s_addc_u32 s11, s3, 0
	s_waitcnt vmcnt(0)
	v_cmp_eq_u32_e32 vcc, v1, v0
	s_and_saveexec_b64 s[6:7], vcc
	s_cbranch_execz .LBB0_255
	s_add_u32 s8, s28, 0x163fc300
	s_addc_u32 s9, s29, 0
	s_mov_b32 s22, 1
	s_mov_b64 s[12:13], 0
	v_mov_b32_e32 v1, 0
	s_branch .LBB0_246

.Lmy_fw_8:
	s_or_b64 exec, exec, s[98:99]
	v_cmp_ne_u32_e32 vcc, v3, v2
	s_and_saveexec_b64 s[4:5], vcc
	s_xor_b64 s[4:5], exec, s[4:5]
	s_cbranch_execz .LBB0_1095
	s_waitcnt lgkmcnt(0)
	v_mov_b32_e32 v1, 0x2000
	global_load_dword v1, v1, s[2:3] offset:1024 sc1
	s_add_u32 s12, s2, 0x2400
	s_addc_u32 s13, s3, 0
	s_waitcnt vmcnt(0)
	v_cmp_eq_u32_e32 vcc, v1, v0
	s_and_saveexec_b64 s[6:7], vcc
	s_cbranch_execz .LBB0_1094
	s_add_u32 s10, s28, 0x163fc300
	s_addc_u32 s11, s29, 0
	s_mov_b32 s24, 1
	s_mov_b64 s[14:15], 0
	v_mov_b32_e32 v1, 0
	s_branch .LBB0_1085
